# long diff-attention loop: both K/V prefetch address blocks (v_mad_i64_i32 + 64-bit chains) replaced by 32-bit offsets with SGPR-base global loads; on top of the LDS/prefetch address rewrite of the sho
# speedup vs baseline: 1.0082x; 1.0072x over previous
.LBB0_273:
	s_waitcnt vmcnt(0)
	s_lshl_b32 s24, s24, 7
	v_lshrrev_b32_e32 v142, 3, v204
	v_lshlrev_b32_e32 v96, 4, v204
	v_and_b32_e32 v96, 0x70, v96
	v_lshl_add_u32 v143, v142, 7, v96
	v_mul_u32_u24_e32 v144, s68, v142
	v_lshl_add_u32 v143, s24, 6, v143
	v_lshl_add_u32 v144, v144, 1, v96
	v_add_u32_e32 v144, s24, v144
	v_lshl_add_u32 v142, s68, 7, v144
	s_nop 0
	global_load_dwordx4 v[130:133], v143, s[50:51]
	s_mov_b64 s[86:87], s[28:29]
	global_load_dwordx4 v[134:137], v143, s[96:97]
	s_nop 0
	global_load_dwordx4 v[138:141], v144, s[70:71]
	s_nop 0
	global_load_dwordx4 v[142:145], v142, s[70:71]

.LBB0_284:
	s_nop 0
	s_lshl_b32 s24, s24, 7
	v_lshrrev_b32_e32 v126, 3, v204
	v_lshlrev_b32_e32 v96, 4, v204
	v_and_b32_e32 v96, 0x70, v96
	v_lshl_add_u32 v127, v126, 7, v96
	v_mul_u32_u24_e32 v128, s60, v126
	v_lshl_add_u32 v127, s24, 6, v127
	v_lshl_add_u32 v128, v128, 1, v96
	v_add_u32_e32 v128, s24, v128
	v_lshl_add_u32 v126, s60, 7, v128
	s_nop 0
	global_load_dwordx4 v[114:117], v127, s[96:97]
	s_mov_b64 s[86:87], s[28:29]
	global_load_dwordx4 v[118:121], v127, s[70:71]
	s_nop 0
	global_load_dwordx4 v[122:125], v128, s[68:69]
	s_nop 0
	global_load_dwordx4 v[126:129], v126, s[68:69]
